# v112 + wave priority 2 for the whole of E1 (upstream tiles win the CU during the E1/E2 overlap), back to 0 at the E1 exit
# baseline (speedup 1.0000x reference)
; __device__ __forceinline__ unsigned my_xcc_id() { return (unsigned)__builtin_amdgcn_s_getreg((3 << 11) | 20) & 7u; }
; template <class F>
; __device__ __forceinline__ void xcd_queue_run(unsigned* qwords, int nper, char* smem_aux, F fn) {
;   volatile int* slot = (volatile int*)smem_aux;
;   const unsigned x = my_xcc_id();
;   for (int dj = 0; dj < 8; dj++) {
;     const int j = (int)((x + dj) & 7u);
; __device__ void phaseE1(const Params& p, char* smem) {
;   int* s_off = (int*)(smem + 2 * GEMM_SMEM);
;   int* s_rb = s_off + 72;
;   moe_prefix(p, s_off, s_rb);
;   xcd_queue_run(p.bar + QW_BASE + 1024, s_rb[NEXP], smem + 2 * GEMM_SMEM + 800, [&](int j, int q) {
.LBB0_1264:
	s_or_b64 exec, exec, s[0:1]
	s_mov_b64 s[0:1], src_shared_base
	s_add_u32 s0, s82, 0x4600
	s_addc_u32 s22, s83, 0
	s_add_i32 s2, 0, 0x10220
	v_mov_b32_e32 v0, s2
	s_waitcnt lgkmcnt(0)
	s_barrier
	ds_read_b32 v153, v0
	v_add_u32_e32 v150, 32, v160
	v_and_b32_e32 v0, 0x100, v128
	v_add_u32_e32 v151, 64, v160
	v_cmp_eq_u32_e64 s[6:7], 0, v0
	v_lshrrev_b32_e32 v0, 1, v150
	v_add_u32_e32 v152, 0x60, v160
	v_and_b32_e32 v156, 0x60, v0
	v_lshrrev_b32_e32 v0, 1, v151
	v_and_b32_e32 v157, 0x60, v0
	v_and_b32_e32 v0, 32, v152
	v_cmp_eq_u32_e64 s[8:9], 0, v0
	v_lshrrev_b32_e32 v0, 1, v152
	v_and_b32_e32 v158, 0x60, v0
	v_lshlrev_b32_e32 v0, 6, v128
	v_and_b32_e32 v1, 32, v133
	s_getreg_b32 s23, hwreg(HW_REG_XCC_ID, 0, 4)
	v_bfe_u32 v154, v128, 3, 5
	v_and_b32_e32 v155, 32, v132
	v_and_b32_e32 v0, 0x13c0, v0
	v_mov_b32_e32 v97, 0
	v_lshlrev_b32_e32 v96, 1, v1
	s_add_u32 s10, s56, 0x80
	s_mov_b32 s3, 0
	v_lshl_add_u64 v[98:99], s[58:59], 0, v[96:97]
	v_lshl_add_u64 v[100:101], s[56:57], 0, v[124:125]
	s_mov_b64 s[4:5], 0x80
	s_addc_u32 s11, s57, 0
	v_or_b32_e32 v159, v155, v154
	s_lshl_b32 s24, s23, 6
	v_or_b32_e32 v172, v156, v154
	v_or_b32_e32 v173, v157, v154
	v_or_b32_e32 v174, v158, v154
	v_lshlrev_b32_e32 v102, 1, v134
	v_mov_b32_e32 v103, v97
	s_add_i32 s25, 0, 0x10124
	v_lshlrev_b32_e32 v175, 1, v0
	s_mov_b32 s26, 0
	s_mov_b32 s32, -1
	s_setprio 2
	s_mov_b32 s51, -1
	s_branch .LBB0_1266

; __device__ __forceinline__ void xcd_barrier(const XcdBarrier& b) {
;   asm volatile("s_waitcnt vmcnt(0)" ::: "memory");
;   __syncthreads();
;   if (threadIdx.x == 0) {
;     unsigned* bar = b.bar;
;     __builtin_amdgcn_s_waitcnt(0);
.LBB0_1290:
	s_setprio 0
	s_waitcnt vmcnt(0)
	s_barrier
	s_and_saveexec_b64 s[72:73], s[34:35]
	s_cbranch_execz .Le1_fin
	s_cmp_lt_i32 s51, 0
	s_cbranch_scc1 .Le1_fin
	s_lshr_b32 s49, s51, 5
	s_lshl_b32 s49, s49, 8
	s_and_b32 s50, s51, 31
	s_lshl_b32 s50, s50, 2
	s_add_u32 s49, s49, s50
	s_addk_i32 s49, 0x4604
	v_mov_b32_e32 v0, s49
	v_mov_b32_e32 v1, 1
	global_atomic_add v0, v1, s[82:83]
